# plus P6: odd workgroups run the ple GEMM before the out-projection GEMM
# baseline (speedup 1.0000x reference)
; __device__ __forceinline__ int opaque_tid() { int t = threadIdx.x; asm volatile("" : "+v"(t)); return t; }
; #define PG8_STAGE(bufoff, gbase, voff) do { _Pragma("unroll") for (int _i = 0; _i < 2; ++_i) \
;         __builtin_amdgcn_global_load_lds((const unsigned*)((const char*)(gbase) + (voff)[_i]), (LAS unsigned*)(lds + (bufoff) + ldsw + _i * 8192), 16, 0, 0); } while (0)
; template <class Epi>
; __device__ __forceinline__ void gemm_phase(LAS unsigned char* lds, const Gemm g, const StaticOrder& S, const Epi& E, const int tid) {
;     const int wid = __builtin_amdgcn_readfirstlane(tid >> 6), lane = tid & 63, wr = wid >> 2, wc = wid & 3, fr = lane & 15, fq = lane >> 4;
;     const int K = g.K, nt = K / BK;
;     unsigned voffA[2], voffB[2];
; #pragma unroll
;     for (int i = 0; i < 2; ++i) { int R, C; stage_rc(tid * 16 + i * 8192, R, C); const int Rb = (R & ~31) + perm32(R & 31);
;         voffA[i] = (unsigned)(R * g.lda + C) * 2u; voffB[i] = (unsigned)(Rb * g.ldb + C) * 2u; }
;     const size_t kstep = (size_t)(BK * 2);
;     const size_t hstepA = (size_t)HALF * g.lda * 2, hstepB = (size_t)HALF * g.ldb * 2;
;     const size_t tstepA = 2 * hstepA, tstepB = 2 * hstepB;
;     const unsigned ldsw = (unsigned)wid * 1024u;
;     const int aoff = lds_byte(wr * 64 + fr, fq * 8), boff = lds_byte(wc * 32 + fr, fq * 8);
;     ...
;     Unit cur, nxt; int ui = 0;
;     if (!S.next(0, cur)) return;
;     f32x4 acc[2][2][4][2];
;     E.init(acc, cur, wr, wc, fr, fq);
;     bf16x8 At[4][2], B0[2][2], B1[2][2];
;     const char* cA = (const char*)g.A + (size_t)cur.pm * tstepA; const char* cB = (const char*)g.Bt + (size_t)cur.pn * tstepB;
;     PG8_STAGE(PG8_SB(0, 0), cB, voffB); PG8_STAGE(PG8_SA(0, 0), cA, voffA); PG8_STAGE(PG8_SB(0, 1), cB + hstepB, voffB); PG8_STAGE(PG8_SA(0, 1), cA + hstepA, voffA);
;     if (wr == 1) PG8_BAR;
;     PG8_WAIT_V(4); PG8_BAR;
;     PG8_STAGE(PG8_SB(1, 0), cB + kstep, voffB); PG8_STAGE(PG8_SA(1, 0), cA + kstep, voffA); PG8_STAGE(PG8_SB(1, 1), cB + hstepB + kstep, voffB);
; __global__ void __launch_bounds__(512, 2) fwd_megakernel(Params p_) {
;     ...
;             { const int tid = opaque_tid(); pg8::Gemm g{MRG, wt + WT_OUT, M_TOK, DM, DM, DM, DM}; pg8::StaticOrder S; S.init(M_TOK, DM, G, bid);
;               EpiOut E{X, p->in[I_BOUT] + (size_t)l * DM, p->in[I_LNG] + (size_t)l * DM, XN, STATS}; pg8::gemm_phase(lds, g, S, E, tid); }
.LBB0_770:
	s_or_b64 exec, exec, s[40:41]
	v_readlane_b32 s4, v253, 0
	v_mov_b32_e32 v0, v246
	v_readlane_b32 s5, v253, 1
	s_waitcnt lgkmcnt(0)
	s_barrier
	v_readlane_b32 s101, v253, 7
	s_nop 0
	s_bfe_u32 s101, s101, 0x10003
.Lp6_head:
	s_load_dwordx4 s[12:15], s[4:5], 0xc8
	v_readlane_b32 s0, v255, 6
	v_readlane_b32 s1, v255, 7
	v_mov_b32_e32 v23, v246
	s_waitcnt lgkmcnt(0)
	s_add_u32 s2, s14, s6
	s_addc_u32 s36, s15, s7
	s_lshl_b64 s[40:41], s[0:1], 11
	v_readlane_b32 s0, v255, 13
	v_readlane_b32 s1, v255, 14
	s_and_b64 vcc, exec, s[0:1]
	v_readfirstlane_b32 s37, v23
	s_cbranch_vccnz .LBB0_820
	s_cmp_eq_u32 s101, 1
	s_cbranch_scc1 .LBB0_820
	v_lshlrev_b32_e32 v0, 4, v23
	v_add_u32_e32 v1, 0x2000, v0
	v_ashrrev_i32_e32 v2, 31, v1
	v_lshrrev_b32_e32 v2, 22, v2
	v_add_u32_e32 v2, v1, v2
	v_ashrrev_i32_e32 v16, 10, v2
	v_mul_i32_i24_e32 v2, 0x400, v16
	v_sub_u32_e32 v1, v1, v2
	v_lshrrev_b32_e32 v2, 4, v1
	s_load_dwordx4 s[8:11], s[4:5], 0x98
	v_bitop3_b32 v1, v2, v1, 32 bitop3:0x6c
	s_add_u32 s38, s14, 0x38d2a000
	v_ashrrev_i32_e32 v2, 31, v1
	s_addc_u32 s39, s15, 0
	v_lshrrev_b32_e32 v2, 26, v2
	s_add_u32 s42, s2, 0x3200000
	v_add_u32_e32 v2, v1, v2
	v_lshlrev_b32_e32 v3, 3, v16
	s_addc_u32 s43, s36, 0
	s_lshl_b64 s[20:21], s[40:41], 2
	v_ashrrev_i32_e32 v17, 6, v2
	v_and_b32_e32 v3, -16, v3
	s_waitcnt lgkmcnt(0)
	s_add_u32 s4, s8, s20
	v_add_u32_e32 v3, v17, v3
	s_addc_u32 s5, s9, s21
	v_and_b32_e32 v4, 3, v17
	s_mov_b32 s9, 0xfffe0
	v_lshrrev_b32_e32 v5, 2, v3
	v_lshlrev_b32_e32 v6, 1, v3
	v_and_b32_e32 v2, 0xc0, v2
	v_and_or_b32 v4, v3, s9, v4
	v_and_b32_e32 v5, 4, v5
	v_and_b32_e32 v6, 24, v6
	v_sub_u32_e32 v1, v1, v2
	v_or3_b32 v4, v4, v5, v6
	v_lshlrev_b32_e32 v5, 5, v16
	v_ashrrev_i16_sdwa v1, v247, sext(v1) dst_sel:DWORD dst_unused:UNUSED_PAD src0_sel:DWORD src1_sel:BYTE_0
	v_and_b32_e32 v5, 32, v5
	v_bfe_i32 v19, v1, 0, 16
	v_add_lshl_u32 v1, v5, v19, 1
	v_lshl_add_u32 v160, v4, 12, v1
	v_lshl_add_u32 v162, v3, 12, v1
	v_bfe_i32 v1, v23, 27, 1
	v_lshrrev_b32_e32 v1, 22, v1
	v_add_u32_e32 v1, v0, v1
	v_and_b32_e32 v1, 0xfffffc00, v1
	v_sub_u32_e32 v0, v0, v1
	v_lshrrev_b32_e32 v1, 4, v0
	v_bitop3_b32 v1, v1, v0, 32 bitop3:0x6c
	v_ashrrev_i32_e32 v0, 31, v0
	v_lshrrev_b32_e32 v0, 26, v0
	v_add_u32_e32 v0, v1, v0
	v_ashrrev_i32_e32 v20, 6, v0
	v_ashrrev_i32_e32 v0, 31, v23
	v_lshrrev_b32_e32 v0, 26, v0
	v_add_u32_e32 v0, v23, v0
	v_ashrrev_i32_e32 v21, 6, v0
	v_lshlrev_b32_e32 v0, 3, v21
	v_and_b32_e32 v0, -16, v0
	v_add_u32_e32 v0, v20, v0
	s_ashr_i32 s3, s37, 6
	v_and_b32_e32 v2, 3, v20
	v_lshrrev_b32_e32 v3, 2, v0
	v_lshlrev_b32_e32 v4, 1, v0
	s_lshl_b32 s44, s3, 10
	s_lshl_b32 s3, s3, 5
	v_and_or_b32 v2, v0, s9, v2
	v_and_b32_e32 v3, 4, v3
	v_and_b32_e32 v4, 24, v4
	s_ashr_i32 s8, s37, 8
	s_and_b32 s3, s3, 0x60
	v_or3_b32 v2, v2, v3, v4
	v_mul_i32_i24_e32 v4, 64, v20
	v_readlane_b32 s16, v254, 27
	v_sub_u32_e32 v1, v1, v4
	v_readlane_b32 s17, v254, 28
	s_add_u32 s9, s4, s16
	v_lshlrev_b32_e32 v3, 5, v21
	v_ashrrev_i16_sdwa v1, v247, sext(v1) dst_sel:DWORD dst_unused:UNUSED_PAD src0_sel:DWORD src1_sel:BYTE_0
	s_addc_u32 s17, s5, s17
	s_lshl_b32 s22, s3, 2
	v_bfe_u32 v18, v23, 4, 2
	v_and_b32_e32 v3, 32, v3
	v_bfe_i32 v22, v1, 0, 16
	s_add_u32 s16, s9, s22
	v_add_lshl_u32 v1, v3, v22, 1
	s_addc_u32 s17, s17, 0
	v_lshlrev_b32_e32 v4, 5, v18
	v_lshl_add_u32 v184, v2, 12, v1
	v_lshl_add_u32 v164, v0, 12, v1
	global_load_dwordx4 v[32:35], v4, s[16:17] offset:16
	global_load_dwordx4 v[36:39], v4, s[16:17]
	global_load_dwordx4 v[0:3], v4, s[16:17] offset:528
	s_nop 0
	global_load_dwordx4 v[4:7], v4, s[16:17] offset:512
	v_readlane_b32 s16, v253, 47
	v_readlane_b32 s17, v253, 48
	s_add_u32 s30, s42, s16
	s_addc_u32 s31, s43, s17
	s_add_i32 s48, s44, 0
	s_add_i32 m0, s48, 0x10000
	v_readlane_b32 s16, v253, 18
	global_load_lds_dwordx4 v184, s[30:31]
	s_add_i32 m0, s48, 0x12000
	v_readlane_b32 s17, v253, 19
	s_add_u32 s34, s38, s16
	global_load_lds_dwordx4 v160, s[30:31]
	s_addc_u32 s35, s39, s17
	s_mov_b32 m0, s48
	s_add_i32 s49, s48, 0x2000
	global_load_lds_dwordx4 v164, s[34:35]
	s_mov_b32 m0, s49
	s_add_u32 s16, s30, 0x80000
	global_load_lds_dwordx4 v162, s[34:35]
	s_addc_u32 s17, s31, 0
	s_add_i32 m0, s48, 0x14000
	v_mov_b32_e32 v161, v185
	global_load_lds_dwordx4 v184, s[16:17]
	s_add_i32 m0, s48, 0x16000
	v_mov_b32_e32 v165, v185
	global_load_lds_dwordx4 v160, s[16:17]
	s_add_u32 s16, s34, 0x80000
	s_addc_u32 s17, s35, 0
	s_add_i32 s50, s48, 0x4000
	s_mov_b32 m0, s50
	s_add_i32 s52, s48, 0x6000
	global_load_lds_dwordx4 v164, s[16:17]
	s_mov_b32 m0, s52
	v_mov_b32_e32 v163, v185
	global_load_lds_dwordx4 v162, s[16:17]
	v_lshl_add_u64 v[14:15], s[30:31], 0, v[184:185]
	v_lshl_add_u64 v[12:13], s[30:31], 0, v[160:161]
	v_lshl_add_u64 v[10:11], s[34:35], 0, v[164:165]
	s_cmp_lg_u32 s8, 1
	v_lshl_add_u64 v[8:9], s[34:35], 0, v[162:163]
	s_cbranch_scc1 .LBB0_773
	s_barrier

; __device__ __forceinline__ int opaque_tid() { int t = threadIdx.x; asm volatile("" : "+v"(t)); return t; }
; #define PG8_STAGE(bufoff, gbase, voff) do { _Pragma("unroll") for (int _i = 0; _i < 2; ++_i) \
;         __builtin_amdgcn_global_load_lds((const unsigned*)((const char*)(gbase) + (voff)[_i]), (LAS unsigned*)(lds + (bufoff) + ldsw + _i * 8192), 16, 0, 0); } while (0)
; #define PG8_WAIT_V(n) asm volatile("s_waitcnt vmcnt(" #n ")" ::: "memory")
; template <class Epi>
; __device__ __forceinline__ void gemm_phase(LAS unsigned char* lds, const Gemm g, const StaticOrder& S, const Epi& E, const int tid) {
;     const int wid = __builtin_amdgcn_readfirstlane(tid >> 6), lane = tid & 63, wr = wid >> 2, wc = wid & 3, fr = lane & 15, fq = lane >> 4;
;     const int K = g.K, nt = K / BK;
;     unsigned voffA[2], voffB[2];
; #pragma unroll
;     for (int i = 0; i < 2; ++i) { int R, C; stage_rc(tid * 16 + i * 8192, R, C); const int Rb = (R & ~31) + perm32(R & 31);
;         voffA[i] = (unsigned)(R * g.lda + C) * 2u; voffB[i] = (unsigned)(Rb * g.ldb + C) * 2u; }
;     const size_t kstep = (size_t)(BK * 2);
;     const size_t hstepA = (size_t)HALF * g.lda * 2, hstepB = (size_t)HALF * g.ldb * 2;
;     const size_t tstepA = 2 * hstepA, tstepB = 2 * hstepB;
;     const unsigned ldsw = (unsigned)wid * 1024u;
;     const int aoff = lds_byte(wr * 64 + fr, fq * 8), boff = lds_byte(wc * 32 + fr, fq * 8);
;     ...
;     Unit cur, nxt; int ui = 0;
;     if (!S.next(0, cur)) return;
;     f32x4 acc[2][2][4][2];
;     E.init(acc, cur, wr, wc, fr, fq);
;     bf16x8 At[4][2], B0[2][2], B1[2][2];
;     const char* cA = (const char*)g.A + (size_t)cur.pm * tstepA; const char* cB = (const char*)g.Bt + (size_t)cur.pn * tstepB;
;     PG8_STAGE(PG8_SB(0, 0), cB, voffB); PG8_STAGE(PG8_SA(0, 0), cA, voffA); PG8_STAGE(PG8_SB(0, 1), cB + hstepB, voffB); PG8_STAGE(PG8_SA(0, 1), cA + hstepA, voffA);
;     if (wr == 1) PG8_BAR;
;     PG8_WAIT_V(4); PG8_BAR;
;     PG8_STAGE(PG8_SB(1, 0), cB + kstep, voffB); PG8_STAGE(PG8_SA(1, 0), cA + kstep, voffA); PG8_STAGE(PG8_SB(1, 1), cB + hstepB + kstep, voffB);
; __global__ void __launch_bounds__(512, 2) fwd_megakernel(Params p_) {
;     ...
;             { const int tid = opaque_tid(); pg8::Gemm g{PB, wt + WT_PLE, M_TOK, DM, PLE, PLE, PLE}; pg8::StaticOrder S; S.init(M_TOK, DM, G, bid);
;               EpiPlain E{PLEB}; pg8::gemm_phase(lds, g, S, E, tid); }
.LBB0_820:
	s_cmp_eq_u32 s101, 3
	s_cbranch_scc1 .LBB0_834
	v_readlane_b32 s0, v255, 13
	s_waitcnt vmcnt(0)
	v_mov_b32_e32 v7, v246
	v_readlane_b32 s1, v255, 14
	s_and_b64 vcc, exec, s[0:1]
	v_readfirstlane_b32 s3, v7
	s_cbranch_vccnz .LBB0_834
	v_lshlrev_b32_e32 v1, 4, v7
	v_add_u32_e32 v0, 0x2000, v1
	s_waitcnt lgkmcnt(1)
	v_ashrrev_i32_e32 v2, 31, v0
	v_lshrrev_b32_e32 v2, 22, v2
	v_add_u32_e32 v2, v0, v2
	v_ashrrev_i32_e32 v2, 10, v2
	s_waitcnt lgkmcnt(0)
	v_mul_i32_i24_e32 v3, 0x400, v2
	v_sub_u32_e32 v0, v0, v3
	v_lshrrev_b32_e32 v3, 4, v0
	v_bitop3_b32 v0, v3, v0, 32 bitop3:0x6c
	v_ashrrev_i32_e32 v3, 31, v0
	v_lshrrev_b32_e32 v3, 26, v3
	v_add_u32_e32 v3, v0, v3
	v_lshlrev_b32_e32 v5, 3, v2
	v_ashrrev_i32_e32 v4, 6, v3
	v_and_b32_e32 v5, -16, v5
	v_and_b32_e32 v3, 0xc0, v3
	v_add_u32_e32 v5, v4, v5
	v_sub_u32_e32 v0, v0, v3
	v_bfe_i32 v3, v7, 27, 1
	v_and_b32_e32 v4, 3, v4
	s_mov_b32 s8, 0x7fffe0
	v_lshrrev_b32_e32 v6, 2, v5
	v_lshlrev_b32_e32 v8, 1, v5
	v_lshlrev_b32_e32 v2, 5, v2
	v_ashrrev_i16_sdwa v0, v247, sext(v0) dst_sel:DWORD dst_unused:UNUSED_PAD src0_sel:DWORD src1_sel:BYTE_0
	v_lshrrev_b32_e32 v3, 22, v3
	v_and_or_b32 v4, v5, s8, v4
	v_and_b32_e32 v6, 4, v6
	v_and_b32_e32 v8, 24, v8
	v_and_b32_e32 v2, 32, v2
	v_bfe_i32 v0, v0, 0, 16
	v_add_u32_e32 v3, v1, v3
	v_or3_b32 v4, v4, v6, v8
	v_add_lshl_u32 v2, v2, v0, 1
	v_and_b32_e32 v3, 0xfffffc00, v3
	v_lshl_add_u32 v0, v4, 9, v2
	v_sub_u32_e32 v1, v1, v3
	v_ashrrev_i32_e32 v4, 31, v7
	v_lshrrev_b32_e32 v3, 4, v1
	v_lshrrev_b32_e32 v4, 26, v4
	v_bitop3_b32 v3, v3, v1, 32 bitop3:0x6c
	v_ashrrev_i32_e32 v1, 31, v1
	v_add_u32_e32 v4, v7, v4
	v_lshrrev_b32_e32 v1, 26, v1
	v_ashrrev_i32_e32 v4, 6, v4
	s_add_u32 s2, s2, 0x4200000
	v_lshl_add_u32 v2, v5, 9, v2
	v_add_u32_e32 v1, v3, v1
	v_lshlrev_b32_e32 v5, 3, v4
	s_addc_u32 s30, s36, 0
	s_ashr_i32 s4, s3, 6
	v_ashrrev_i32_e32 v1, 6, v1
	v_and_b32_e32 v5, -16, v5
	s_ashr_i32 s5, s3, 8
	s_lshl_b32 s31, s4, 10
	v_add_u32_e32 v5, v1, v5
	v_and_b32_e32 v6, 3, v1
	v_mul_i32_i24_e32 v1, 64, v1
	s_add_u32 s34, s14, 0x4cd2a000
	v_sub_u32_e32 v1, v3, v1
	s_addc_u32 s35, s15, 0
	v_and_or_b32 v6, v5, s8, v6
	v_lshrrev_b32_e32 v8, 2, v5
	v_lshlrev_b32_e32 v9, 1, v5
	v_lshlrev_b32_e32 v4, 5, v4
	v_ashrrev_i16_sdwa v1, v247, sext(v1) dst_sel:DWORD dst_unused:UNUSED_PAD src0_sel:DWORD src1_sel:BYTE_0
	v_readlane_b32 s8, v253, 37
	v_and_b32_e32 v8, 4, v8
	v_and_b32_e32 v9, 24, v9
	v_and_b32_e32 v4, 32, v4
	v_bfe_i32 v1, v1, 0, 16
	v_readlane_b32 s9, v253, 38
	s_add_u32 s24, s2, s8
	v_or3_b32 v6, v6, v8, v9
	v_add_lshl_u32 v1, v4, v1, 1
	s_addc_u32 s25, s30, s9
	s_add_i32 s36, s31, 0
	v_lshl_add_u32 v184, v6, 9, v1
	s_add_i32 m0, s36, 0x10000
	v_readlane_b32 s8, v253, 35
	global_load_lds_dwordx4 v184, s[24:25]
	s_add_i32 m0, s36, 0x12000
	v_readlane_b32 s9, v253, 36
	s_add_u32 s22, s34, s8
	v_lshl_add_u32 v4, v5, 9, v1
	global_load_lds_dwordx4 v0, s[24:25]
	s_addc_u32 s23, s35, s9
	s_mov_b32 m0, s36
	s_add_i32 s37, s36, 0x2000
	global_load_lds_dwordx4 v4, s[22:23]
	s_mov_b32 m0, s37
	s_add_u32 s8, s24, 0x10000
	global_load_lds_dwordx4 v2, s[22:23]
	s_addc_u32 s9, s25, 0
	s_add_i32 m0, s36, 0x14000
	s_nop 0
	global_load_lds_dwordx4 v184, s[8:9]
	s_add_i32 m0, s36, 0x16000
	s_nop 0
	global_load_lds_dwordx4 v0, s[8:9]
	s_add_u32 s8, s22, 0x10000
	s_addc_u32 s9, s23, 0
	s_add_i32 s38, s36, 0x4000
	s_mov_b32 m0, s38
	s_add_i32 s39, s36, 0x6000
	global_load_lds_dwordx4 v4, s[8:9]
	s_mov_b32 m0, s39
	s_cmp_lg_u32 s5, 1
	global_load_lds_dwordx4 v2, s[8:9]
	s_cbranch_scc1 .LBB0_823
	s_barrier

; __device__ __forceinline__ int opaque_tid() { int t = threadIdx.x; asm volatile("" : "+v"(t)); return t; }
;     __device__ __forceinline__ void init(AccMut acc, const Unit& u, int wr, int wc, int fr, int fq) const { acc_bias(acc, bias + u.pn * 256 + wc * 32 + 8 * fq); }
;     __device__ __forceinline__ void init(AccMut acc, const Unit&, int, int, int, int) const { acc_zero(acc); }
;     __device__ __forceinline__ void init(AccMut acc, const Unit&, int, int, int, int) const { acc_zero(acc); }
;     __device__ __forceinline__ void init(AccMut acc, const Unit& u, int wr, int wc, int fr, int fq) const { acc_bias(acc, bias + u.pn * 256 + wc * 32 + 8 * fq); }
;     __device__ __forceinline__ void init(AccMut acc, const Unit&, int, int, int, int) const { acc_zero(acc); }
;     __device__ __forceinline__ void init(AccMut acc, const Unit&, int, int, int, int) const { acc_zero(acc); }
; __global__ void __launch_bounds__(512, 2) fwd_megakernel(Params p_) {
;     ...
;             { const int tid = opaque_tid(); pg8::Gemm g{PB, wt + WT_PLE, M_TOK, DM, PLE, PLE, PLE}; pg8::StaticOrder S; S.init(M_TOK, DM, G, bid);
;               EpiPlain E{PLEB}; pg8::gemm_phase(lds, g, S, E, tid); }
;         }
.LBB0_834:
	s_cmp_eq_u32 s101, 1
	s_cbranch_scc0 .Lp6_cont
	s_mov_b32 s101, 3
	v_readlane_b32 s4, v253, 0
	v_readlane_b32 s5, v253, 1
	s_nop 3
	s_branch .Lp6_head
